# FoX loop: LDS-DMA issue and K fragment reads moved behind the first PV MFMAs of the iteration (matrix pipe starts right after the barrier); m0 save/restore dropped
# baseline (speedup 1.0000x reference)
.LBB0_178:
	s_barrier
.LBB0_180:
	s_cmp_gt_i32 s47, s46
	s_cbranch_scc1 .LBB0_188
	s_cmp_lg_u32 s46, s47
	s_cbranch_scc1 .Lfx_body
	v_add_u32_e32 v1, s48, v189
	ds_read_b128 v[126:129], v1 offset:32768
	ds_read_b128 v[106:109], v1 offset:40960
	ds_read_b128 v[98:101], v1 offset:33792
	ds_read_b128 v[102:105], v1 offset:41984
	ds_read_b128 v[86:89], v1 offset:34816
	ds_read_b128 v[94:97], v1 offset:43008
	ds_read_b128 v[82:85], v1 offset:35840
	ds_read_b128 v[90:93], v1 offset:44032
	ds_read_b128 v[34:37], v175
	ds_read_b128 v[38:41], v175 offset:16
	ds_read_b128 v[42:45], v175 offset:64
	ds_read_b128 v[46:49], v175 offset:80
	ds_read_b128 v[50:53], v175 offset:128
	ds_read_b128 v[54:57], v175 offset:144
	ds_read_b128 v[58:61], v175 offset:192
	ds_read_b128 v[62:65], v175 offset:208
	s_waitcnt lgkmcnt(0)
	v_mfma_f32_32x32x16_bf16 v[34:49], v[126:129], v[66:69], v[34:49]
	v_mfma_f32_32x32x16_bf16 v[50:65], v[106:109], v[66:69], v[50:65]
	v_mfma_f32_32x32x16_bf16 v[34:49], v[98:101], v[70:73], v[34:49]
	v_mfma_f32_32x32x16_bf16 v[50:65], v[102:105], v[70:73], v[50:65]
	v_mfma_f32_32x32x16_bf16 v[34:49], v[86:89], v[74:77], v[34:49]
	v_mfma_f32_32x32x16_bf16 v[50:65], v[94:97], v[74:77], v[50:65]
	v_mfma_f32_32x32x16_bf16 v[34:49], v[82:85], v[78:81], v[34:49]
	v_mfma_f32_32x32x16_bf16 v[50:65], v[90:93], v[78:81], v[50:65]
	s_nop 1
	v_add_u32_e32 v1, s50, v166
	v_add_u32_e32 v163, 0xe0, v1
	v_add_u32_e32 v162, 0xc0, v1
	v_cmp_le_i32_e32 vcc, v163, v186
	s_nop 6
	v_cndmask_b32_e32 v50, v239, v50, vcc
	v_cmp_lt_i32_e32 vcc, v162, v186
	s_nop 1
	v_cndmask_b32_e32 v35, v239, v35, vcc
	v_cmp_le_i32_e32 vcc, v162, v186
	v_add_u32_e32 v162, 0xe1, v1
	s_nop 0
	v_cndmask_b32_e32 v34, v239, v34, vcc
	v_cmp_le_i32_e32 vcc, v162, v186
	v_add_u32_e32 v162, 0xc2, v1
	s_nop 0
	v_cndmask_b32_e32 v51, v239, v51, vcc
	v_cmp_le_i32_e32 vcc, v162, v186
	v_add_u32_e32 v162, 0xe2, v1
	s_nop 0
	v_cndmask_b32_e32 v36, v239, v36, vcc
	v_cmp_le_i32_e32 vcc, v162, v186
	v_add_u32_e32 v162, 0xc3, v1
	s_nop 0
	v_cndmask_b32_e32 v52, v239, v52, vcc
	v_cmp_le_i32_e32 vcc, v162, v186
	v_add_u32_e32 v162, 0xe3, v1
	s_nop 0
	v_cndmask_b32_e32 v37, v239, v37, vcc
	v_cmp_le_i32_e32 vcc, v162, v186
	v_add_u32_e32 v162, 0xc4, v1
	s_nop 0
	v_cndmask_b32_e32 v53, v239, v53, vcc
	v_cmp_le_i32_e32 vcc, v162, v186
	v_add_u32_e32 v162, 0xe4, v1
	s_nop 0
	v_cndmask_b32_e32 v38, v239, v38, vcc
	v_cmp_le_i32_e32 vcc, v162, v186
	v_add_u32_e32 v162, 0xc5, v1
	s_nop 0
	v_cndmask_b32_e32 v54, v239, v54, vcc
	v_cmp_le_i32_e32 vcc, v162, v186
	v_add_u32_e32 v162, 0xe5, v1
	s_nop 0
	v_cndmask_b32_e32 v39, v239, v39, vcc
	v_cmp_le_i32_e32 vcc, v162, v186
	v_add_u32_e32 v162, 0xc6, v1
	s_nop 0
	v_cndmask_b32_e32 v55, v239, v55, vcc
	v_cmp_le_i32_e32 vcc, v162, v186
	v_add_u32_e32 v162, 0xe6, v1
	s_nop 0
	v_cndmask_b32_e32 v40, v239, v40, vcc
	v_cmp_le_i32_e32 vcc, v162, v186
	v_add_u32_e32 v162, 0xc7, v1
	s_nop 0
	v_cndmask_b32_e32 v56, v239, v56, vcc
	v_cmp_le_i32_e32 vcc, v162, v186
	v_add_u32_e32 v162, 0xe7, v1
	s_nop 0
	v_cndmask_b32_e32 v41, v239, v41, vcc
	v_cmp_le_i32_e32 vcc, v162, v186
	v_add_u32_e32 v162, 0xd0, v1
	s_nop 0
	v_cndmask_b32_e32 v57, v239, v57, vcc
	v_cmp_le_i32_e32 vcc, v162, v186
	v_add_u32_e32 v162, 0xf0, v1
	s_nop 0
	v_cndmask_b32_e32 v42, v239, v42, vcc
	v_cmp_le_i32_e32 vcc, v162, v186
	v_add_u32_e32 v162, 0xd1, v1
	s_nop 0
	v_cndmask_b32_e32 v58, v239, v58, vcc
	v_cmp_le_i32_e32 vcc, v162, v186
	v_add_u32_e32 v162, 0xf1, v1
	s_nop 0
	v_cndmask_b32_e32 v43, v239, v43, vcc
	v_cmp_le_i32_e32 vcc, v162, v186
	v_add_u32_e32 v162, 0xd2, v1
	s_nop 0
	v_cndmask_b32_e32 v59, v239, v59, vcc
	v_cmp_le_i32_e32 vcc, v162, v186
	v_add_u32_e32 v162, 0xf2, v1
	s_nop 0
	v_cndmask_b32_e32 v44, v239, v44, vcc
	v_cmp_le_i32_e32 vcc, v162, v186
	v_add_u32_e32 v162, 0xd3, v1
	s_nop 0
	v_cndmask_b32_e32 v60, v239, v60, vcc
	v_cmp_le_i32_e32 vcc, v162, v186
	v_add_u32_e32 v162, 0xf3, v1
	s_nop 0
	v_cndmask_b32_e32 v45, v239, v45, vcc
	v_cmp_le_i32_e32 vcc, v162, v186
	v_add_u32_e32 v162, 0xd4, v1
	s_nop 0
	v_cndmask_b32_e32 v61, v239, v61, vcc
	v_cmp_le_i32_e32 vcc, v162, v186
	v_add_u32_e32 v162, 0xf4, v1
	s_nop 0
	v_cndmask_b32_e32 v46, v239, v46, vcc
	v_cmp_le_i32_e32 vcc, v162, v186
	v_add_u32_e32 v162, 0xd5, v1
	s_nop 0
	v_cndmask_b32_e32 v62, v239, v62, vcc
	v_cmp_le_i32_e32 vcc, v162, v186
	v_add_u32_e32 v162, 0xf5, v1
	s_nop 0
	v_cndmask_b32_e32 v47, v239, v47, vcc
	v_cmp_le_i32_e32 vcc, v162, v186
	v_add_u32_e32 v162, 0xd6, v1
	s_nop 0
	v_cndmask_b32_e32 v63, v239, v63, vcc
	v_cmp_le_i32_e32 vcc, v162, v186
	v_add_u32_e32 v162, 0xf6, v1
	s_nop 0
	v_cndmask_b32_e32 v48, v239, v48, vcc
	v_cmp_le_i32_e32 vcc, v162, v186
	v_add_u32_e32 v162, 0xd7, v1
	v_add_u32_e32 v1, 0xf7, v1
	v_cndmask_b32_e32 v64, v239, v64, vcc
	v_cmp_le_i32_e32 vcc, v162, v186
	s_nop 1
	v_cndmask_b32_e32 v49, v239, v49, vcc
	v_cmp_le_i32_e32 vcc, v1, v186
	s_nop 1
	v_cndmask_b32_e32 v65, v239, v65, vcc
	v_mov_b32_e32 v163, v0
	v_max3_f32 v1, v34, v35, v36
	v_max3_f32 v208, v50, v51, v52
	v_max3_f32 v1, v1, v37, v38
	v_max3_f32 v1, v1, v39, v40
	v_max3_f32 v1, v1, v41, v42
	v_max3_f32 v1, v1, v43, v44
	v_max3_f32 v1, v1, v45, v46
	v_max3_f32 v1, v1, v47, v48
	v_max3_f32 v208, v208, v53, v54
	v_max3_f32 v208, v208, v55, v56
	v_max3_f32 v208, v208, v57, v58
	v_max3_f32 v208, v208, v59, v60
	v_max3_f32 v208, v208, v61, v62
	v_max3_f32 v208, v208, v63, v64
	v_max3_f32 v208, v208, v65, v49
	v_max_f32_e32 v1, v1, v208
	ds_bpermute_b32 v209, v203, v1
	s_waitcnt lgkmcnt(0)
	v_max_f32_e32 v1, v1, v209
	v_cvt_pk_bf16_f32 v209, v1, v1
	v_lshlrev_b32_e32 v200, 16, v209
	v_xor_b32_e32 v209, 0x8000, v209
	v_and_b32_e32 v209, 0xffff, v209
	v_cndmask_b32_e64 v162, 0, v209, s[16:17]
	v_sub_f32_e32 v34, v34, v200
	v_sub_f32_e32 v35, v35, v200
	v_sub_f32_e32 v36, v36, v200
	v_sub_f32_e32 v37, v37, v200
	v_sub_f32_e32 v38, v38, v200
	v_sub_f32_e32 v39, v39, v200
	v_sub_f32_e32 v40, v40, v200
	v_sub_f32_e32 v41, v41, v200
	v_sub_f32_e32 v42, v42, v200
	v_sub_f32_e32 v43, v43, v200
	v_sub_f32_e32 v44, v44, v200
	v_sub_f32_e32 v45, v45, v200
	v_sub_f32_e32 v46, v46, v200
	v_sub_f32_e32 v47, v47, v200
	v_sub_f32_e32 v48, v48, v200
	v_sub_f32_e32 v49, v49, v200
	v_sub_f32_e32 v50, v50, v200
	v_sub_f32_e32 v51, v51, v200
	v_sub_f32_e32 v52, v52, v200
	v_sub_f32_e32 v53, v53, v200
	v_sub_f32_e32 v54, v54, v200
	v_sub_f32_e32 v55, v55, v200
	v_sub_f32_e32 v56, v56, v200
	v_sub_f32_e32 v57, v57, v200
	v_sub_f32_e32 v58, v58, v200
	v_sub_f32_e32 v59, v59, v200
	v_sub_f32_e32 v60, v60, v200
	v_sub_f32_e32 v61, v61, v200
	v_sub_f32_e32 v62, v62, v200
	v_sub_f32_e32 v63, v63, v200
	v_sub_f32_e32 v64, v64, v200
	v_sub_f32_e32 v65, v65, v200
.Lfx_body:
	s_add_i32 s37, s49, 0xc000
	s_and_b32 s37, s37, 0xc000
	v_add_u32_e32 v194, s37, v189
	v_add_u32_e32 v195, 0xffffff00, v175
	v_max_i32_e32 v195, v195, v0
	v_mfma_f32_32x32x16_bf16 v[18:33], v[158:161], v[122:125], v[18:33]
	v_exp_f32_e32 v208, v34
	v_exp_f32_e32 v209, v35
	v_exp_f32_e32 v210, v36
	v_exp_f32_e32 v211, v37
	ds_read_b128 v[158:161], v194 offset:36864
	s_cmp_lt_u32 s47, 3
	s_cbranch_scc1 .Lfx_nodma_body
	s_add_i32 s78, s44, s50
	s_lshl_b64 s[38:39], s[78:79], s41
	s_and_b32 s37, s49, 0xc000
	v_lshl_add_u64 v[126:127], s[38:39], 1, v[180:181]
	s_add_i32 s38, s45, s37
	s_mov_b32 m0, s38
	s_nop 0
	global_load_lds_dwordx4 v[126:127], off
	s_mov_b32 s37, s79
	v_lshl_add_u64 v[126:127], v[126:127], 0, s[36:37]
	s_addk_i32 s38, 0x2000
	s_mov_b32 m0, s38
	s_nop 0
	global_load_lds_dwordx4 v[126:127], off
.Lfx_nodma_body:
	v_mfma_f32_32x32x16_bf16 v[18:33], v[154:157], v[118:121], v[18:33]
	v_exp_f32_e32 v212, v38
	v_exp_f32_e32 v213, v39
	v_exp_f32_e32 v214, v40
	v_exp_f32_e32 v215, v41
	ds_read_b128 v[154:157], v194 offset:37888
	s_add_i32 s37, s49, 0x18000
	s_and_b32 s37, s37, 0xc000
	v_add_u32_e32 v1, s37, v189
	ds_read_b128 v[126:129], v1 offset:32768
	ds_read_b128 v[106:109], v1 offset:40960
	ds_read_b128 v[98:101], v1 offset:33792
	ds_read_b128 v[102:105], v1 offset:41984
	ds_read_b128 v[86:89], v1 offset:34816
	ds_read_b128 v[94:97], v1 offset:43008
	ds_read_b128 v[82:85], v1 offset:35840
	ds_read_b128 v[90:93], v1 offset:44032
	v_mfma_f32_32x32x16_bf16 v[2:17], v[142:145], v[122:125], v[2:17]
	v_exp_f32_e32 v216, v42
	v_exp_f32_e32 v217, v43
	v_exp_f32_e32 v218, v44
	v_exp_f32_e32 v219, v45
	ds_read_b128 v[142:145], v194 offset:38912
	v_mfma_f32_32x32x16_bf16 v[18:33], v[150:153], v[114:117], v[18:33]
	v_exp_f32_e32 v220, v46
	v_exp_f32_e32 v221, v47
	v_exp_f32_e32 v222, v48
	v_exp_f32_e32 v223, v49
	ds_read_b128 v[150:153], v194 offset:45056
	ds_read_b128 v[34:37], v195
	ds_read_b128 v[38:41], v195 offset:16
	ds_read_b128 v[42:45], v195 offset:64
	ds_read_b128 v[46:49], v195 offset:80
	v_mfma_f32_32x32x16_bf16 v[2:17], v[138:141], v[118:121], v[2:17]
	v_exp_f32_e32 v224, v50
	v_exp_f32_e32 v225, v51
	v_exp_f32_e32 v226, v52
	v_exp_f32_e32 v227, v53
	ds_read_b128 v[138:141], v194 offset:39936
	v_mfma_f32_32x32x16_bf16 v[18:33], v[146:149], v[110:113], v[18:33]
	v_exp_f32_e32 v228, v54
	v_exp_f32_e32 v229, v55
	v_exp_f32_e32 v230, v56
	v_exp_f32_e32 v231, v57
	ds_read_b128 v[146:149], v194 offset:46080
	v_mfma_f32_32x32x16_bf16 v[2:17], v[134:137], v[114:117], v[2:17]
	v_exp_f32_e32 v244, v58
	v_exp_f32_e32 v245, v59
	v_exp_f32_e32 v246, v60
	v_exp_f32_e32 v247, v61
	ds_read_b128 v[134:137], v194 offset:47104
	v_mfma_f32_32x32x16_bf16 v[2:17], v[130:133], v[110:113], v[2:17]
	v_exp_f32_e32 v248, v62
	v_exp_f32_e32 v249, v63
	v_exp_f32_e32 v250, v64
	v_exp_f32_e32 v251, v65
	ds_read_b128 v[130:133], v194 offset:48128
	ds_read_b128 v[50:53], v195 offset:128
	ds_read_b128 v[54:57], v195 offset:144
	ds_read_b128 v[58:61], v195 offset:192
	ds_read_b128 v[62:65], v195 offset:208
	v_add_f32_e32 v110, v208, v209
	v_add_f32_e32 v111, v210, v211
	v_add_f32_e32 v112, v212, v213
	v_add_f32_e32 v113, v214, v215
	s_waitcnt lgkmcnt(8)
	v_mfma_f32_32x32x16_bf16 v[34:49], v[126:129], v[66:69], v[34:49]
	v_add_f32_e32 v110, v216, v110
	v_add_f32_e32 v111, v217, v111
	v_add_f32_e32 v112, v218, v112
	s_waitcnt lgkmcnt(0)
	v_mfma_f32_32x32x16_bf16 v[50:65], v[106:109], v[66:69], v[50:65]
	v_add_f32_e32 v113, v219, v113
	v_add_f32_e32 v110, v220, v110
	v_add_f32_e32 v111, v221, v111
	v_mfma_f32_32x32x16_bf16 v[34:49], v[98:101], v[70:73], v[34:49]
	v_add_f32_e32 v112, v222, v112
	v_add_f32_e32 v113, v223, v113
	v_add_f32_e32 v110, v224, v110
	v_mfma_f32_32x32x16_bf16 v[50:65], v[102:105], v[70:73], v[50:65]
	v_add_f32_e32 v111, v225, v111
	v_add_f32_e32 v112, v226, v112
	v_add_f32_e32 v113, v227, v113
	v_mfma_f32_32x32x16_bf16 v[34:49], v[86:89], v[74:77], v[34:49]
	v_add_f32_e32 v110, v228, v110
	v_add_f32_e32 v111, v229, v111
	v_add_f32_e32 v112, v230, v112
	v_mfma_f32_32x32x16_bf16 v[50:65], v[94:97], v[74:77], v[50:65]
	v_add_f32_e32 v113, v231, v113
	v_add_f32_e32 v110, v244, v110
	v_add_f32_e32 v111, v245, v111
	v_mfma_f32_32x32x16_bf16 v[34:49], v[82:85], v[78:81], v[34:49]
	v_add_f32_e32 v112, v246, v112
	v_add_f32_e32 v113, v247, v113
	v_add_f32_e32 v110, v248, v110
	v_mfma_f32_32x32x16_bf16 v[50:65], v[90:93], v[78:81], v[50:65]
	v_add_f32_e32 v111, v249, v111
	v_add_f32_e32 v112, v250, v112
	v_add_f32_e32 v113, v251, v113
	v_mfma_f32_32x32x16_bf16 v[34:49], v[196:199], v[162:165], v[34:49]
	v_mfma_f32_32x32x16_bf16 v[50:65], v[196:199], v[162:165], v[50:65]
	v_add_f32_e32 v110, v110, v111
	v_add_f32_e32 v112, v112, v113
	v_add_f32_e32 v114, v110, v112
	v_cmp_lt_f32_e32 vcc, 0x49800000, v114
	s_cbranch_vccnz .Lfx_rare

.LBB0_188:
	s_cmp_lt_u32 s47, 3
	s_cbranch_scc1 .Lfx_nodma_skip
	s_add_i32 s78, s44, s50
	s_lshl_b64 s[38:39], s[78:79], s41
	s_and_b32 s37, s49, 0xc000
	v_lshl_add_u64 v[208:209], s[38:39], 1, v[180:181]
	s_add_i32 s38, s45, s37
	s_mov_b32 m0, s38
	s_nop 0
	global_load_lds_dwordx4 v[208:209], off
	s_mov_b32 s37, s79
	v_lshl_add_u64 v[208:209], v[208:209], 0, s[36:37]
	s_addk_i32 s38, 0x2000
	s_mov_b32 m0, s38
	s_nop 0
	global_load_lds_dwordx4 v[208:209], off
